# v9: ret_fix dependent-load prefetch on top of v8
# speedup vs baseline: 1.0266x; 1.0033x over previous
; __device__ __forceinline__ void ret_fix(bf16* ST, const bf16* FS, const float* dexp, int vb, int nb, int tid) {
;     ...
; #pragma unroll 4
;         for (int i = 0; i < 16; ++i) { const int id = tid + 512 * i;
;             v4u f[3];
; #pragma unroll
;             for (int k = 0; k < 3; ++k) if (k < ncar) { const int so = dir == 0 ? sg - 1 - k : sg + 1 + k; f[k] = ((const v4u*)(FS + ((size_t)(so * 8 + h) * 2 + dir) * 65536))[id]; }
;             v4u l0 = {0u, 0u, 0u, 0u}; if (loc) l0 = ((const v4u*)dst)[id];
.LBB0_710:
	v_add_u32_e32 v60, s29, v1
	v_ashrrev_i32_e32 v61, 31, v60
	v_lshl_add_u64 v[100:101], v[60:61], 4, s[42:43]
	s_mov_b64 s[100:101], 0x2000
	s_cmp_lg_u64 s[16:17], 0
	s_cbranch_scc0 .Lrf_pf_a
	v_lshl_add_u64 v[102:103], v[60:61], 4, s[36:37]
	global_load_dwordx4 v[104:107], v[102:103], off
	v_lshl_add_u64 v[102:103], v[102:103], 0, s[100:101]
	global_load_dwordx4 v[104:107], v[102:103], off
	v_lshl_add_u64 v[102:103], v[102:103], 0, s[100:101]
	global_load_dwordx4 v[104:107], v[102:103], off
	v_lshl_add_u64 v[102:103], v[102:103], 0, s[100:101]
	global_load_dwordx4 v[104:107], v[102:103], off
.Lrf_pf_a:
	s_cmp_lg_u64 s[50:51], 0
	s_cbranch_scc0 .Lrf_pf_done
	v_lshl_add_u64 v[102:103], v[100:101], 0, s[54:55]
	global_load_dwordx4 v[104:107], v[102:103], off
	v_lshl_add_u64 v[102:103], v[102:103], 0, s[100:101]
	global_load_dwordx4 v[104:107], v[102:103], off
	v_lshl_add_u64 v[102:103], v[102:103], 0, s[100:101]
	global_load_dwordx4 v[104:107], v[102:103], off
	v_lshl_add_u64 v[102:103], v[102:103], 0, s[100:101]
	global_load_dwordx4 v[104:107], v[102:103], off
	s_cmp_lg_u64 s[56:57], 0
	s_cbranch_scc0 .Lrf_pf_done
	v_lshl_add_u64 v[102:103], v[100:101], 0, s[58:59]
	global_load_dwordx4 v[104:107], v[102:103], off
	v_lshl_add_u64 v[102:103], v[102:103], 0, s[100:101]
	global_load_dwordx4 v[104:107], v[102:103], off
	v_lshl_add_u64 v[102:103], v[102:103], 0, s[100:101]
	global_load_dwordx4 v[104:107], v[102:103], off
	v_lshl_add_u64 v[102:103], v[102:103], 0, s[100:101]
	global_load_dwordx4 v[104:107], v[102:103], off
	s_cmp_lg_u64 s[64:65], 0
	s_cbranch_scc0 .Lrf_pf_done
	v_lshl_add_u64 v[102:103], v[100:101], 0, s[66:67]
	global_load_dwordx4 v[104:107], v[102:103], off
	v_lshl_add_u64 v[102:103], v[102:103], 0, s[100:101]
	global_load_dwordx4 v[104:107], v[102:103], off
	v_lshl_add_u64 v[102:103], v[102:103], 0, s[100:101]
	global_load_dwordx4 v[104:107], v[102:103], off
	v_lshl_add_u64 v[102:103], v[102:103], 0, s[100:101]
	global_load_dwordx4 v[104:107], v[102:103], off
.Lrf_pf_done:
	v_cndmask_b32_e64 v38, 0, 1, s[50:51]
	v_cmp_ne_u32_e64 s[4:5], 1, v38
	s_andn2_b64 vcc, exec, s[50:51]
	v_lshl_add_u64 v[50:51], v[60:61], 4, s[42:43]
	s_cbranch_vccnz .LBB0_712
	v_lshl_add_u64 v[2:3], v[50:51], 0, s[54:55]
	global_load_dwordx4 v[2:5], v[2:3], off
	s_waitcnt vmcnt(0)
	v_mov_b64_e32 v[24:25], v[12:13]
	v_mov_b64_e32 v[36:37], v[12:13]
	v_mov_b64_e32 v[22:23], v[10:11]
	v_mov_b64_e32 v[20:21], v[8:9]
	v_mov_b64_e32 v[18:19], v[6:7]
	v_mov_b64_e32 v[34:35], v[10:11]
	v_mov_b64_e32 v[32:33], v[8:9]
	v_mov_b64_e32 v[30:31], v[6:7]
	v_mov_b64_e32 v[16:17], v[4:5]
	v_mov_b64_e32 v[14:15], v[2:3]
	v_mov_b64_e32 v[28:29], v[4:5]
	v_mov_b64_e32 v[26:27], v[2:3]
	s_branch .LBB0_713

; __global__ void __launch_bounds__(NT, 2) fwd_kernel(Args args_unused) {
	.amdhsa_kernel _Z10fwd_kernel4Args
		.amdhsa_group_segment_fixed_size 0
		.amdhsa_private_segment_fixed_size 0
		.amdhsa_kernarg_size 496
		.amdhsa_user_sgpr_count 2
		.amdhsa_user_sgpr_dispatch_ptr 0
		.amdhsa_user_sgpr_queue_ptr 0
		.amdhsa_user_sgpr_kernarg_segment_ptr 1
		.amdhsa_user_sgpr_dispatch_id 0
		.amdhsa_user_sgpr_kernarg_preload_length 0
		.amdhsa_user_sgpr_kernarg_preload_offset 0
		.amdhsa_user_sgpr_private_segment_size 0
		.amdhsa_uses_dynamic_stack 0
		.amdhsa_enable_private_segment 0
		.amdhsa_system_sgpr_workgroup_id_x 1
		.amdhsa_system_sgpr_workgroup_id_y 0
		.amdhsa_system_sgpr_workgroup_id_z 0
		.amdhsa_system_sgpr_workgroup_info 0
		.amdhsa_system_vgpr_workitem_id 0
		.amdhsa_next_free_vgpr 253
		.amdhsa_next_free_sgpr 102
		.amdhsa_accum_offset 256
		.amdhsa_reserve_vcc 1
		.amdhsa_float_round_mode_32 0
		.amdhsa_float_round_mode_16_64 0
		.amdhsa_float_denorm_mode_32 3
		.amdhsa_float_denorm_mode_16_64 3
		.amdhsa_dx10_clamp 1
		.amdhsa_ieee_mode 1
		.amdhsa_fp16_overflow 0
		.amdhsa_tg_split 0
		.amdhsa_exception_fp_ieee_invalid_op 0
		.amdhsa_exception_fp_denorm_src 0
		.amdhsa_exception_fp_ieee_div_zero 0
		.amdhsa_exception_fp_ieee_overflow 0
		.amdhsa_exception_fp_ieee_underflow 0
		.amdhsa_exception_fp_ieee_inexact 0
		.amdhsa_exception_int_div_zero 0
	.end_amdhsa_kernel

; __global__ void __launch_bounds__(NT, 2) fwd_kernel(Args args_unused) {
amdhsa.kernels:
  - .agpr_count:     0
    .args:
      - .offset:         0
        .size:           240
        .value_kind:     by_value
      - .offset:         240
        .size:           4
        .value_kind:     hidden_block_count_x
      - .offset:         244
        .size:           4
        .value_kind:     hidden_block_count_y
      - .offset:         248
        .size:           4
        .value_kind:     hidden_block_count_z
      - .offset:         252
        .size:           2
        .value_kind:     hidden_group_size_x
      - .offset:         254
        .size:           2
        .value_kind:     hidden_group_size_y
      - .offset:         256
        .size:           2
        .value_kind:     hidden_group_size_z
      - .offset:         258
        .size:           2
        .value_kind:     hidden_remainder_x
      - .offset:         260
        .size:           2
        .value_kind:     hidden_remainder_y
      - .offset:         262
        .size:           2
        .value_kind:     hidden_remainder_z
      - .offset:         280
        .size:           8
        .value_kind:     hidden_global_offset_x
      - .offset:         288
        .size:           8
        .value_kind:     hidden_global_offset_y
      - .offset:         296
        .size:           8
        .value_kind:     hidden_global_offset_z
      - .offset:         304
        .size:           2
        .value_kind:     hidden_grid_dims
      - .offset:         360
        .size:           4
        .value_kind:     hidden_dynamic_lds_size
    .group_segment_fixed_size: 0
    .kernarg_segment_align: 8
    .kernarg_segment_size: 496
    .language:       OpenCL C
    .language_version:
      - 2
      - 0
    .max_flat_workgroup_size: 512
    .name:           _Z10fwd_kernel4Args
    .private_segment_fixed_size: 0
    .sgpr_count:     108
    .sgpr_spill_count: 86
    .symbol:         _Z10fwd_kernel4Args.kd
    .uniform_work_group_size: 1
    .uses_dynamic_stack: false
    .vgpr_count:     253
    .vgpr_spill_count: 0
    .wavefront_size: 64
